# FFN layer-1 weight conversion moved from the ROW1 phase into the idle second half of the grid in the last round of the GLA input GEMM
# speedup vs baseline: 1.0137x; 1.0128x over previous
.LBB0_243:
	s_cmp_eq_u32 s22, 5
	s_cbranch_scc0 .Lcv_ret_gin
	s_cmp_ge_u32 s2, 128
	s_cbranch_scc0 .Lcv_ret_gin
	v_readlane_b32 s24, v251, 29
	v_readlane_b32 s25, v251, 30
	s_movk_i32 s13, 0x82
	s_nop 3
	s_branch .Lcv_entry

.Lrw_done:
.LBB0_306:
	s_or_b64 exec, exec, s[40:41]
	v_readlane_b32 s16, v254, 31
	v_readlane_b32 s17, v254, 32
	v_readlane_b32 s66, v254, 35
	v_readlane_b32 s67, v254, 36
	s_nop 1
	s_mov_b64 s[64:65], s[16:17]
	s_cmp_eq_u32 s22, 13
	s_cbranch_scc1 .Lcv_r2
	s_cmp_eq_u32 s22, 17
	s_cbranch_scc1 .Lcv_r3
	s_branch .Lcv_ret_row

.Lcv_rgo:
	s_movk_i32 s13, 0x101
	s_nop 3
	s_branch .Lcv_entry

.LBB0_564:
	v_readlane_b32 s24, v251, 51
	v_readlane_b32 s25, v251, 52
	s_movk_i32 s13, 0x100
	s_nop 3
	s_branch .Lcv_entry

.Lcv_entry:
	s_add_u32 s28, s20, 0x4000
	s_addc_u32 s29, s21, 0
	v_lshrrev_b32_e32 v38, 3, v220
	v_and_b32_e32 v39, 7, v220
	v_lshlrev_b32_e32 v39, 3, v39
	s_mov_b32 s0, 5632
	v_mul_lo_u32 v36, v38, s0
	v_add_lshl_u32 v36, v36, v39, 2
	s_mov_b32 s0, 1024
	v_mul_lo_u32 v37, v38, s0
	v_add_lshl_u32 v37, v37, v39, 1
	s_movk_i32 s0, 65
	v_mul_lo_u32 v40, v39, s0
	v_add_lshl_u32 v40, v40, v38, 2
	v_mul_lo_u32 v38, v38, s0
	v_add_lshl_u32 v38, v38, v39, 2
	v_mov_b32_e32 v39, v40
	v_add_u32_e32 v40, 1040, v39
	s_mov_b32 s7, s2
	s_and_b32 s0, s13, 3
	s_cmp_eq_u32 s0, 2
	s_cselect_b32 s0, 128, 0
	s_sub_i32 s7, s7, s0
	s_cmp_lt_u32 s7, 1408
	s_cbranch_scc0 .Lcv_gu_end
	s_and_b32 s0, s7, 15
	s_lshr_b32 s1, s7, 4
	s_mul_i32 s9, s0, 360448
	s_lshr_b32 s10, s1, 2
	s_lshl_b32 s10, s10, 7
	s_add_i32 s9, s9, s10
	s_and_b32 s10, s1, 1
	s_lshl_b32 s10, s10, 6
	s_add_i32 s9, s9, s10
	s_bitcmp1_b32 s1, 1
	s_cselect_b32 s10, 2816, 0
	s_add_i32 s9, s9, s10
	s_lshl_b32 s9, s9, 2
	s_add_u32 s38, s24, s9
	s_addc_u32 s39, s25, 0
	global_load_dwordx4 v[0:3], v36, s[38:39]
	global_load_dwordx4 v[4:7], v36, s[38:39] offset:16
	s_and_b32 s5, s13, 0x3fc
	s_add_i32 s5, s5, s7
	s_cmp_lt_u32 s5, 1408
	s_cbranch_scc0 .Lcv_gu_loop
	s_and_b32 s0, s5, 15
	s_lshr_b32 s1, s5, 4
	s_mul_i32 s9, s0, 360448
	s_lshr_b32 s10, s1, 2
	s_lshl_b32 s10, s10, 7
	s_add_i32 s9, s9, s10
	s_and_b32 s10, s1, 1
	s_lshl_b32 s10, s10, 6
	s_add_i32 s9, s9, s10
	s_bitcmp1_b32 s1, 1
	s_cselect_b32 s10, 2816, 0
	s_add_i32 s9, s9, s10
	s_lshl_b32 s9, s9, 2
	s_add_u32 s38, s24, s9
	s_addc_u32 s39, s25, 0
	global_load_dwordx4 v[8:11], v36, s[38:39]
	global_load_dwordx4 v[12:15], v36, s[38:39] offset:16
.Lcv_gu_loop:
	s_and_b32 s5, s13, 0x3fc
	s_lshl_b32 s5, s5, 1
	s_add_i32 s5, s5, s7
	s_cmp_lt_u32 s5, 1408
	s_cbranch_scc0 .Lcv_gu_ni0
	s_and_b32 s0, s5, 15
	s_lshr_b32 s1, s5, 4
	s_mul_i32 s9, s0, 360448
	s_lshr_b32 s10, s1, 2
	s_lshl_b32 s10, s10, 7
	s_add_i32 s9, s9, s10
	s_and_b32 s10, s1, 1
	s_lshl_b32 s10, s10, 6
	s_add_i32 s9, s9, s10
	s_bitcmp1_b32 s1, 1
	s_cselect_b32 s10, 2816, 0
	s_add_i32 s9, s9, s10
	s_lshl_b32 s9, s9, 2
	s_add_u32 s38, s24, s9
	s_addc_u32 s39, s25, 0
	global_load_dwordx4 v[16:19], v36, s[38:39]
	global_load_dwordx4 v[20:23], v36, s[38:39] offset:16
	s_waitcnt vmcnt(4)
	s_branch .Lcv_gu_go0

.Lcv_gu_go0:
	ds_write2_b32 v38, v0, v1 offset0:0 offset1:1
	ds_write2_b32 v38, v2, v3 offset0:2 offset1:3
	ds_write2_b32 v38, v4, v5 offset0:4 offset1:5
	ds_write2_b32 v38, v6, v7 offset0:6 offset1:7
	s_waitcnt lgkmcnt(0)
	s_barrier
	ds_read2_b32 v[28:29], v39 offset1:65
	ds_read2_b32 v[30:31], v39 offset0:130 offset1:195
	ds_read2_b32 v[32:33], v40 offset1:65
	ds_read2_b32 v[34:35], v40 offset0:130 offset1:195
	s_and_b32 s0, s7, 15
	s_lshr_b32 s1, s7, 4
	s_lshl_b32 s1, s1, 16
	s_lshl_b32 s0, s0, 6
	s_add_i32 s1, s1, s0
	s_lshl_b32 s1, s1, 1
	s_add_u32 s40, s28, s1
	s_addc_u32 s41, s29, 0
	s_waitcnt lgkmcnt(2)
	v_cvt_pk_bf16_f32 v24, v28, v29
	v_cvt_pk_bf16_f32 v25, v30, v31
	s_waitcnt lgkmcnt(0)
	v_cvt_pk_bf16_f32 v26, v32, v33
	v_cvt_pk_bf16_f32 v27, v34, v35
	global_store_dwordx4 v37, v[24:27], s[40:41]
	s_and_b32 s9, s13, 0x3fc
	s_add_i32 s7, s7, s9
	s_cmp_lt_u32 s7, 1408
	s_cbranch_scc0 .Lcv_gu_end
	v_add_u32_e32 v38, 16640, v38
	v_add_u32_e32 v39, 16640, v39
	v_add_u32_e32 v40, 16640, v40
	s_and_b32 s5, s13, 0x3fc
	s_lshl_b32 s5, s5, 1
	s_add_i32 s5, s5, s7
	s_cmp_lt_u32 s5, 1408
	s_cbranch_scc0 .Lcv_gu_ni1
	s_and_b32 s0, s5, 15
	s_lshr_b32 s1, s5, 4
	s_mul_i32 s9, s0, 360448
	s_lshr_b32 s10, s1, 2
	s_lshl_b32 s10, s10, 7
	s_add_i32 s9, s9, s10
	s_and_b32 s10, s1, 1
	s_lshl_b32 s10, s10, 6
	s_add_i32 s9, s9, s10
	s_bitcmp1_b32 s1, 1
	s_cselect_b32 s10, 2816, 0
	s_add_i32 s9, s9, s10
	s_lshl_b32 s9, s9, 2
	s_add_u32 s38, s24, s9
	s_addc_u32 s39, s25, 0
	global_load_dwordx4 v[0:3], v36, s[38:39]
	global_load_dwordx4 v[4:7], v36, s[38:39] offset:16
	s_waitcnt vmcnt(4)
	s_branch .Lcv_gu_go1

.Lcv_gu_go1:
	ds_write2_b32 v38, v8, v9 offset0:0 offset1:1
	ds_write2_b32 v38, v10, v11 offset0:2 offset1:3
	ds_write2_b32 v38, v12, v13 offset0:4 offset1:5
	ds_write2_b32 v38, v14, v15 offset0:6 offset1:7
	s_waitcnt lgkmcnt(0)
	s_barrier
	ds_read2_b32 v[28:29], v39 offset1:65
	ds_read2_b32 v[30:31], v39 offset0:130 offset1:195
	ds_read2_b32 v[32:33], v40 offset1:65
	ds_read2_b32 v[34:35], v40 offset0:130 offset1:195
	s_and_b32 s0, s7, 15
	s_lshr_b32 s1, s7, 4
	s_lshl_b32 s1, s1, 16
	s_lshl_b32 s0, s0, 6
	s_add_i32 s1, s1, s0
	s_lshl_b32 s1, s1, 1
	s_add_u32 s40, s28, s1
	s_addc_u32 s41, s29, 0
	s_waitcnt lgkmcnt(2)
	v_cvt_pk_bf16_f32 v24, v28, v29
	v_cvt_pk_bf16_f32 v25, v30, v31
	s_waitcnt lgkmcnt(0)
	v_cvt_pk_bf16_f32 v26, v32, v33
	v_cvt_pk_bf16_f32 v27, v34, v35
	global_store_dwordx4 v37, v[24:27], s[40:41]
	s_and_b32 s9, s13, 0x3fc
	s_add_i32 s7, s7, s9
	s_cmp_lt_u32 s7, 1408
	s_cbranch_scc0 .Lcv_gu_end
	v_add_u32_e32 v38, 16640, v38
	v_add_u32_e32 v39, 16640, v39
	v_add_u32_e32 v40, 16640, v40
	s_and_b32 s5, s13, 0x3fc
	s_lshl_b32 s5, s5, 1
	s_add_i32 s5, s5, s7
	s_cmp_lt_u32 s5, 1408
	s_cbranch_scc0 .Lcv_gu_ni2
	s_and_b32 s0, s5, 15
	s_lshr_b32 s1, s5, 4
	s_mul_i32 s9, s0, 360448
	s_lshr_b32 s10, s1, 2
	s_lshl_b32 s10, s10, 7
	s_add_i32 s9, s9, s10
	s_and_b32 s10, s1, 1
	s_lshl_b32 s10, s10, 6
	s_add_i32 s9, s9, s10
	s_bitcmp1_b32 s1, 1
	s_cselect_b32 s10, 2816, 0
	s_add_i32 s9, s9, s10
	s_lshl_b32 s9, s9, 2
	s_add_u32 s38, s24, s9
	s_addc_u32 s39, s25, 0
	global_load_dwordx4 v[8:11], v36, s[38:39]
	global_load_dwordx4 v[12:15], v36, s[38:39] offset:16
	s_waitcnt vmcnt(4)
	s_branch .Lcv_gu_go2

.Lcv_gu_go2:
	ds_write2_b32 v38, v16, v17 offset0:0 offset1:1
	ds_write2_b32 v38, v18, v19 offset0:2 offset1:3
	ds_write2_b32 v38, v20, v21 offset0:4 offset1:5
	ds_write2_b32 v38, v22, v23 offset0:6 offset1:7
	s_waitcnt lgkmcnt(0)
	s_barrier
	ds_read2_b32 v[28:29], v39 offset1:65
	ds_read2_b32 v[30:31], v39 offset0:130 offset1:195
	ds_read2_b32 v[32:33], v40 offset1:65
	ds_read2_b32 v[34:35], v40 offset0:130 offset1:195
	s_and_b32 s0, s7, 15
	s_lshr_b32 s1, s7, 4
	s_lshl_b32 s1, s1, 16
	s_lshl_b32 s0, s0, 6
	s_add_i32 s1, s1, s0
	s_lshl_b32 s1, s1, 1
	s_add_u32 s40, s28, s1
	s_addc_u32 s41, s29, 0
	s_waitcnt lgkmcnt(2)
	v_cvt_pk_bf16_f32 v24, v28, v29
	v_cvt_pk_bf16_f32 v25, v30, v31
	s_waitcnt lgkmcnt(0)
	v_cvt_pk_bf16_f32 v26, v32, v33
	v_cvt_pk_bf16_f32 v27, v34, v35
	global_store_dwordx4 v37, v[24:27], s[40:41]
	s_and_b32 s9, s13, 0x3fc
	s_add_i32 s7, s7, s9
	s_cmp_lt_u32 s7, 1408
	s_cbranch_scc0 .Lcv_gu_end
	v_subrev_u32_e32 v38, 33280, v38
	v_subrev_u32_e32 v39, 33280, v39
	v_subrev_u32_e32 v40, 33280, v40
	s_branch .Lcv_gu_loop
.Lcv_gu_end:
	s_barrier
	s_and_b32 s0, s13, 3
	s_cmp_eq_u32 s0, 0
	s_cbranch_scc1 .Lcv_d0
	s_cmp_eq_u32 s22, 5
	s_cbranch_scc1 .Lcv_d1
	s_cmp_eq_u32 s22, 13
	s_cbranch_scc1 .Lcv_d2
	v_readlane_b32 s24, v251, 55
	v_readlane_b32 s25, v251, 56
	s_branch .Lcv_dgo

.Lcv_dgo:
	s_add_u32 s28, s20, 0xb04000
	s_addc_u32 s29, s21, 0
	v_lshrrev_b32_e32 v38, 3, v220
	v_and_b32_e32 v39, 7, v220
	v_lshlrev_b32_e32 v39, 3, v39
	s_mov_b32 s0, 1024
	v_mul_lo_u32 v36, v38, s0
	v_add_lshl_u32 v36, v36, v39, 2
	s_mov_b32 s0, 2816
	v_mul_lo_u32 v37, v38, s0
	v_add_lshl_u32 v37, v37, v39, 1
	s_movk_i32 s0, 65
	v_mul_lo_u32 v40, v39, s0
	v_add_lshl_u32 v40, v40, v38, 2
	v_mul_lo_u32 v38, v38, s0
	v_add_lshl_u32 v38, v38, v39, 2
	v_mov_b32_e32 v39, v40
	v_add_u32_e32 v40, 1040, v39
	s_mov_b32 s7, s2
	s_and_b32 s0, s13, 3
	s_cmp_eq_u32 s0, 2
	s_cselect_b32 s0, 128, 0
	s_sub_i32 s7, s7, s0
	s_cmp_lt_u32 s7, 704
	s_cbranch_scc0 .Lcv_dn_end
	s_mul_i32 s1, s7, 47663
	s_lshr_b32 s1, s1, 21
	s_mul_i32 s0, s1, 44
	s_sub_i32 s0, s7, s0
	s_lshl_b32 s9, s0, 16
	s_lshl_b32 s10, s1, 6
	s_add_i32 s9, s9, s10
	s_lshl_b32 s9, s9, 2
	s_add_u32 s38, s24, s9
	s_addc_u32 s39, s25, 0
	global_load_dwordx4 v[0:3], v36, s[38:39]
	global_load_dwordx4 v[4:7], v36, s[38:39] offset:16
	s_and_b32 s5, s13, 0x3fc
	s_add_i32 s5, s5, s7
	s_cmp_lt_u32 s5, 704
	s_cbranch_scc0 .Lcv_dn_loop
	s_mul_i32 s1, s5, 47663
	s_lshr_b32 s1, s1, 21
	s_mul_i32 s0, s1, 44
	s_sub_i32 s0, s5, s0
	s_lshl_b32 s9, s0, 16
	s_lshl_b32 s10, s1, 6
	s_add_i32 s9, s9, s10
	s_lshl_b32 s9, s9, 2
	s_add_u32 s38, s24, s9
	s_addc_u32 s39, s25, 0
	global_load_dwordx4 v[8:11], v36, s[38:39]
	global_load_dwordx4 v[12:15], v36, s[38:39] offset:16
.Lcv_dn_loop:
	s_and_b32 s5, s13, 0x3fc
	s_lshl_b32 s5, s5, 1
	s_add_i32 s5, s5, s7
	s_cmp_lt_u32 s5, 704
	s_cbranch_scc0 .Lcv_dn_ni0
	s_mul_i32 s1, s5, 47663
	s_lshr_b32 s1, s1, 21
	s_mul_i32 s0, s1, 44
	s_sub_i32 s0, s5, s0
	s_lshl_b32 s9, s0, 16
	s_lshl_b32 s10, s1, 6
	s_add_i32 s9, s9, s10
	s_lshl_b32 s9, s9, 2
	s_add_u32 s38, s24, s9
	s_addc_u32 s39, s25, 0
	global_load_dwordx4 v[16:19], v36, s[38:39]
	global_load_dwordx4 v[20:23], v36, s[38:39] offset:16
	s_waitcnt vmcnt(4)
	s_branch .Lcv_dn_go0

.Lcv_dn_go0:
	ds_write2_b32 v38, v0, v1 offset0:0 offset1:1
	ds_write2_b32 v38, v2, v3 offset0:2 offset1:3
	ds_write2_b32 v38, v4, v5 offset0:4 offset1:5
	ds_write2_b32 v38, v6, v7 offset0:6 offset1:7
	s_waitcnt lgkmcnt(0)
	s_barrier
	ds_read2_b32 v[28:29], v39 offset1:65
	ds_read2_b32 v[30:31], v39 offset0:130 offset1:195
	ds_read2_b32 v[32:33], v40 offset1:65
	ds_read2_b32 v[34:35], v40 offset0:130 offset1:195
	s_mul_i32 s1, s7, 47663
	s_lshr_b32 s1, s1, 21
	s_mul_i32 s0, s1, 44
	s_sub_i32 s0, s7, s0
	s_mul_i32 s1, s1, 180224
	s_lshl_b32 s0, s0, 6
	s_add_i32 s1, s1, s0
	s_lshl_b32 s1, s1, 1
	s_add_u32 s40, s28, s1
	s_addc_u32 s41, s29, 0
	s_waitcnt lgkmcnt(2)
	v_cvt_pk_bf16_f32 v24, v28, v29
	v_cvt_pk_bf16_f32 v25, v30, v31
	s_waitcnt lgkmcnt(0)
	v_cvt_pk_bf16_f32 v26, v32, v33
	v_cvt_pk_bf16_f32 v27, v34, v35
	global_store_dwordx4 v37, v[24:27], s[40:41]
	s_and_b32 s9, s13, 0x3fc
	s_add_i32 s7, s7, s9
	s_cmp_lt_u32 s7, 704
	s_cbranch_scc0 .Lcv_dn_end
	v_add_u32_e32 v38, 16640, v38
	v_add_u32_e32 v39, 16640, v39
	v_add_u32_e32 v40, 16640, v40
	s_and_b32 s5, s13, 0x3fc
	s_lshl_b32 s5, s5, 1
	s_add_i32 s5, s5, s7
	s_cmp_lt_u32 s5, 704
	s_cbranch_scc0 .Lcv_dn_ni1
	s_mul_i32 s1, s5, 47663
	s_lshr_b32 s1, s1, 21
	s_mul_i32 s0, s1, 44
	s_sub_i32 s0, s5, s0
	s_lshl_b32 s9, s0, 16
	s_lshl_b32 s10, s1, 6
	s_add_i32 s9, s9, s10
	s_lshl_b32 s9, s9, 2
	s_add_u32 s38, s24, s9
	s_addc_u32 s39, s25, 0
	global_load_dwordx4 v[0:3], v36, s[38:39]
	global_load_dwordx4 v[4:7], v36, s[38:39] offset:16
	s_waitcnt vmcnt(4)
	s_branch .Lcv_dn_go1

.Lcv_dn_go1:
	ds_write2_b32 v38, v8, v9 offset0:0 offset1:1
	ds_write2_b32 v38, v10, v11 offset0:2 offset1:3
	ds_write2_b32 v38, v12, v13 offset0:4 offset1:5
	ds_write2_b32 v38, v14, v15 offset0:6 offset1:7
	s_waitcnt lgkmcnt(0)
	s_barrier
	ds_read2_b32 v[28:29], v39 offset1:65
	ds_read2_b32 v[30:31], v39 offset0:130 offset1:195
	ds_read2_b32 v[32:33], v40 offset1:65
	ds_read2_b32 v[34:35], v40 offset0:130 offset1:195
	s_mul_i32 s1, s7, 47663
	s_lshr_b32 s1, s1, 21
	s_mul_i32 s0, s1, 44
	s_sub_i32 s0, s7, s0
	s_mul_i32 s1, s1, 180224
	s_lshl_b32 s0, s0, 6
	s_add_i32 s1, s1, s0
	s_lshl_b32 s1, s1, 1
	s_add_u32 s40, s28, s1
	s_addc_u32 s41, s29, 0
	s_waitcnt lgkmcnt(2)
	v_cvt_pk_bf16_f32 v24, v28, v29
	v_cvt_pk_bf16_f32 v25, v30, v31
	s_waitcnt lgkmcnt(0)
	v_cvt_pk_bf16_f32 v26, v32, v33
	v_cvt_pk_bf16_f32 v27, v34, v35
	global_store_dwordx4 v37, v[24:27], s[40:41]
	s_and_b32 s9, s13, 0x3fc
	s_add_i32 s7, s7, s9
	s_cmp_lt_u32 s7, 704
	s_cbranch_scc0 .Lcv_dn_end
	v_add_u32_e32 v38, 16640, v38
	v_add_u32_e32 v39, 16640, v39
	v_add_u32_e32 v40, 16640, v40
	s_and_b32 s5, s13, 0x3fc
	s_lshl_b32 s5, s5, 1
	s_add_i32 s5, s5, s7
	s_cmp_lt_u32 s5, 704
	s_cbranch_scc0 .Lcv_dn_ni2
	s_mul_i32 s1, s5, 47663
	s_lshr_b32 s1, s1, 21
	s_mul_i32 s0, s1, 44
	s_sub_i32 s0, s5, s0
	s_lshl_b32 s9, s0, 16
	s_lshl_b32 s10, s1, 6
	s_add_i32 s9, s9, s10
	s_lshl_b32 s9, s9, 2
	s_add_u32 s38, s24, s9
	s_addc_u32 s39, s25, 0
	global_load_dwordx4 v[8:11], v36, s[38:39]
	global_load_dwordx4 v[12:15], v36, s[38:39] offset:16
	s_waitcnt vmcnt(4)
	s_branch .Lcv_dn_go2

.Lcv_dn_go2:
	ds_write2_b32 v38, v16, v17 offset0:0 offset1:1
	ds_write2_b32 v38, v18, v19 offset0:2 offset1:3
	ds_write2_b32 v38, v20, v21 offset0:4 offset1:5
	ds_write2_b32 v38, v22, v23 offset0:6 offset1:7
	s_waitcnt lgkmcnt(0)
	s_barrier
	ds_read2_b32 v[28:29], v39 offset1:65
	ds_read2_b32 v[30:31], v39 offset0:130 offset1:195
	ds_read2_b32 v[32:33], v40 offset1:65
	ds_read2_b32 v[34:35], v40 offset0:130 offset1:195
	s_mul_i32 s1, s7, 47663
	s_lshr_b32 s1, s1, 21
	s_mul_i32 s0, s1, 44
	s_sub_i32 s0, s7, s0
	s_mul_i32 s1, s1, 180224
	s_lshl_b32 s0, s0, 6
	s_add_i32 s1, s1, s0
	s_lshl_b32 s1, s1, 1
	s_add_u32 s40, s28, s1
	s_addc_u32 s41, s29, 0
	s_waitcnt lgkmcnt(2)
	v_cvt_pk_bf16_f32 v24, v28, v29
	v_cvt_pk_bf16_f32 v25, v30, v31
	s_waitcnt lgkmcnt(0)
	v_cvt_pk_bf16_f32 v26, v32, v33
	v_cvt_pk_bf16_f32 v27, v34, v35
	global_store_dwordx4 v37, v[24:27], s[40:41]
	s_and_b32 s9, s13, 0x3fc
	s_add_i32 s7, s7, s9
	s_cmp_lt_u32 s7, 704
	s_cbranch_scc0 .Lcv_dn_end
	v_subrev_u32_e32 v38, 33280, v38
	v_subrev_u32_e32 v39, 33280, v39
	v_subrev_u32_e32 v40, 33280, v40
	s_branch .Lcv_dn_loop
.Lcv_dn_end:
	s_barrier
	s_and_b32 s0, s13, 3
	s_cmp_eq_u32 s0, 0
	s_cbranch_scc1 .Lcv_ret_pro
	s_cmp_eq_u32 s0, 2
	s_cbranch_scc1 .Lcv_ret_gin
	s_branch .Lcv_ret_row
